# gated-delta consumer waves at raised priority over the producer waves sharing their SIMDs (static priority, on the balanced version)
# speedup vs baseline: 1.0029x; 1.0029x over previous
; __device__ __forceinline__ void xcd_barrier(const XcdBarrier& b) {
;     asm volatile("s_waitcnt vmcnt(0)" ::: "memory");
;     __syncthreads();
;     if (threadIdx.x == 0) {
;         unsigned* bar = b.bar;
;         __builtin_amdgcn_s_waitcnt(0);
;         unsigned nloc = b.st[0], nx = b.st[1];
;         if (nloc == 0u) { xcd_barrier_complete(bar, b.x, nloc, nx); b.st[0] = nloc; b.st[1] = nx; }
; __global__ void __launch_bounds__(512, 2) hybrid_fwd(Params P) {
;     ...
;         if (++rep >= nrep) { rep = 0; ++ph; }
;         if (ph < P.ph_hi) { if (ph == 1 && rep == 0) cg::this_grid().sync(); else xcd_barrier(xbar); }
.LBB0_566:
	s_setprio 0
	s_add_i32 s94, s68, 1
	s_cmp_ge_i32 s94, s95
	s_mov_b64 s[0:1], -1
	s_mov_b64 s[10:11], s[86:87]
	s_cbranch_scc1 .LBB0_10
	s_waitcnt vmcnt(0)
	s_waitcnt lgkmcnt(0)
	s_barrier
	s_mov_b64 s[0:1], exec
	v_readlane_b32 s10, v247, 3
	v_readlane_b32 s11, v247, 4
	s_and_b64 s[10:11], s[0:1], s[10:11]
	s_mov_b64 exec, s[10:11]
	s_cbranch_execz .LBB0_620
	v_readlane_b32 s2, v245, 12
	s_waitcnt vmcnt(0) expcnt(0) lgkmcnt(0)
	s_nop 0
	v_mov_b32_e32 v0, s2
	ds_read_b32 v2, v0
	v_readlane_b32 s2, v245, 13
	s_waitcnt lgkmcnt(0)
	v_cmp_ne_u32_e32 vcc, 0, v2
	v_mov_b32_e32 v0, s2
	ds_read_b32 v0, v0
	s_cbranch_vccnz .LBB0_584
	v_readlane_b32 s12, v247, 1
	v_readlane_b32 s13, v247, 2
	s_load_dwordx2 s[10:11], s[12:13], 0x4
	s_mov_b32 s4, 1
	s_waitcnt lgkmcnt(0)
	s_mul_i32 s2, s10, s33
	s_mul_i32 s2, s2, s11
	s_branch .LBB0_572

; #define LAS __attribute__((address_space(3)))
; __device__ __forceinline__ void delta_unit(const Params& P, LAS unsigned char* lds, int li, bool sample, int b, int h, int half, const int tid) {
;     ...
;         } else if (j >= 1 && j <= NC) {
;             LAS float* qs = (LAS float*)(lds + ((j - 1) & 1) * SET); LAS float* ks = qs + 2048; LAS float* vs = qs + 4096; LAS float* os = qs + 6144; LAS float* sc = qs + 8192;
;             const int ntok = min(MX_CH, L - (j - 1) * MX_CH);
;             f32x4 kA0, kA1, qA0, qA1, kB0, kB1, qB0, qB1; float vA, vB; f32x2 gA, gB;
;             kA0 = *(const LAS f32x4*)(ks + 8 * dq); kA1 = *(const LAS f32x4*)(ks + 8 * dq + 4); qA0 = *(const LAS f32x4*)(qs + 8 * dq); qA1 = *(const LAS f32x4*)(qs + 8 * dq + 4);
;             vA = vs[e]; gA = *(const LAS f32x2*)(sc);
.LBB0_648:
	s_setprio 1
	s_add_i32 s0, s14, -1
	s_cmpk_gt_u32 s0, 0x7f
	v_mov_b32_e32 v63, v83
	v_mov_b32_e32 v62, v84
	v_mov_b32_e32 v65, v86
	v_mov_b32_e32 v64, v87
	v_mov_b32_e32 v67, v88
	v_mov_b32_e32 v66, v89
	v_mov_b32_e32 v69, v91
	v_mov_b32_e32 v68, v81
	s_cbranch_scc1 .LBB0_651
	s_bitcmp1_b32 s0, 0
	s_cselect_b32 s1, 0x8100, 0
	s_add_i32 s0, s1, 0
	s_waitcnt lgkmcnt(4)
	v_mov_b32_e32 v24, s0
	v_lshl_add_u32 v96, v78, 2, s0
	v_lshl_add_u32 v97, v76, 2, s0
	s_waitcnt lgkmcnt(1)
	ds_read_b64 v[70:71], v24 offset:32768
	ds_read_b32 v100, v97 offset:16384
	ds_read_b128 v[24:27], v96
	ds_read_b128 v[28:31], v96 offset:16
	ds_read_b128 v[32:35], v96 offset:8208
	ds_read_b128 v[36:39], v96 offset:8192
	v_add_u32_e32 v98, s1, v90
	v_add_u32_e32 v99, s1, v92
	s_add_i32 s1, s0, 0x8008
	s_mov_b32 s25, -2
	v_mov_b32_e32 v68, v81
	v_mov_b32_e32 v69, v91
	v_mov_b32_e32 v66, v89
	v_mov_b32_e32 v67, v88
	v_mov_b32_e32 v64, v87
	v_mov_b32_e32 v65, v86
	v_mov_b32_e32 v62, v84
	v_mov_b32_e32 v63, v83
